# cmp1 GEMM k-loop: A-loader conversion deferred to the other half-iteration so the source loads fly a whole half (was load+wait+convert in the same half)
# baseline (speedup 1.0000x reference)
.LBB0_435:
	s_add_i32 s9, s8, 2
	s_min_u32 s16, s9, 31
	v_lshl_or_b32 v126, s16, 6, v158
	v_lshlrev_b32_e32 v127, 2, v126
	v_mov_b32_e32 v169, 0
	global_load_dwordx4 v[236:239], v127, s[40:41] offset:16
	global_load_dwordx4 v[232:235], v127, s[40:41]
	v_mov_b32_e32 v94, 0
	v_mov_b32_e32 v95, 0
	v_mov_b32_e32 v96, 0
	v_mov_b32_e32 v97, 0
	s_and_saveexec_b64 s[4:5], s[52:53]
	v_lshl_add_u32 v0, s16, 7, v160
	v_lshl_add_u64 v[94:95], v[176:177], 0, v[0:1]
	global_load_dwordx4 v[94:97], v[94:95], off
	s_or_b64 exec, exec, s[4:5]
	v_mov_b32_e32 v106, 0
	v_mov_b32_e32 v107, 0
	v_mov_b32_e32 v108, 0
	v_mov_b32_e32 v109, 0
	s_and_saveexec_b64 s[4:5], s[56:57]
	v_lshl_add_u32 v0, s16, 7, v164
	v_lshl_add_u64 v[104:105], v[178:179], 0, v[0:1]
	global_load_dwordx4 v[106:109], v[104:105], off
	s_or_b64 exec, exec, s[4:5]
	v_mov_b32_e32 v102, 0
	v_mov_b32_e32 v103, 0
	v_mov_b32_e32 v104, 0
	v_mov_b32_e32 v105, 0
	s_and_saveexec_b64 s[4:5], s[58:59]
	v_lshl_add_u32 v0, s16, 7, v168
	v_lshl_add_u64 v[102:103], v[180:181], 0, v[0:1]
	global_load_dwordx4 v[102:105], v[102:103], off
	s_or_b64 exec, exec, s[4:5]
	v_mov_b32_e32 v122, 0
	v_mov_b32_e32 v123, 0
	v_mov_b32_e32 v124, 0
	v_mov_b32_e32 v125, 0
	s_and_saveexec_b64 s[4:5], s[60:61]
	v_lshl_add_u32 v0, s16, 7, v172
	v_lshl_add_u64 v[122:123], v[182:183], 0, v[0:1]
	global_load_dwordx4 v[122:125], v[122:123], off
	s_or_b64 exec, exec, s[4:5]
	v_or_b32_e32 v0, v126, v162
	v_lshl_add_u64 v[98:99], v[0:1], 1, s[54:55]
	global_load_dwordx4 v[98:101], v[98:99], off
	v_or_b32_e32 v0, v126, v166
	v_lshl_add_u64 v[114:115], v[0:1], 1, s[54:55]
	global_load_dwordx4 v[114:117], v[114:115], off
	v_or_b32_e32 v0, v126, v170
	v_lshl_add_u64 v[118:119], v[0:1], 1, s[54:55]
	global_load_dwordx4 v[118:121], v[118:119], off
	ds_read_b128 v[214:217], v159
	ds_read_b128 v[218:221], v161 offset:18432
	ds_read_b128 v[222:225], v159 offset:4608
	v_or_b32_e32 v0, v126, v174
	v_lshl_add_u64 v[126:127], v[0:1], 1, s[54:55]
	s_min_u32 s16, s8, 28
	s_waitcnt lgkmcnt(1)
	v_mfma_f32_32x32x16_bf16 v[50:65], v[214:217], v[218:221], v[50:65]
	s_add_i32 s16, s16, 3
	s_waitcnt lgkmcnt(0)
	v_mfma_f32_32x32x16_bf16 v[18:33], v[222:225], v[218:221], v[18:33]
	ds_read_b128 v[218:221], v161 offset:23040
	s_waitcnt lgkmcnt(0)
	v_mfma_f32_32x32x16_bf16 v[34:49], v[214:217], v[218:221], v[34:49]
	v_mfma_f32_32x32x16_bf16 v[2:17], v[222:225], v[218:221], v[2:17]
	ds_read_b128 v[214:217], v159 offset:32
	ds_read_b128 v[218:221], v161 offset:18464
	ds_read_b128 v[222:225], v163 offset:4608
	s_waitcnt lgkmcnt(1)
	v_mfma_f32_32x32x16_bf16 v[50:65], v[214:217], v[218:221], v[50:65]
	s_waitcnt lgkmcnt(0)
	v_mfma_f32_32x32x16_bf16 v[18:33], v[222:225], v[218:221], v[18:33]
	ds_read_b128 v[218:221], v161 offset:23072
	s_waitcnt lgkmcnt(0)
	v_mfma_f32_32x32x16_bf16 v[34:49], v[214:217], v[218:221], v[34:49]
	v_mfma_f32_32x32x16_bf16 v[2:17], v[222:225], v[218:221], v[2:17]
	ds_read_b128 v[214:217], v159 offset:64
	ds_read_b128 v[218:221], v161 offset:18496
	global_load_dwordx4 v[126:129], v[126:127], off
	ds_read_b128 v[222:225], v165 offset:4608
	s_waitcnt lgkmcnt(1)
	v_mfma_f32_32x32x16_bf16 v[50:65], v[214:217], v[218:221], v[50:65]
	s_waitcnt lgkmcnt(0)
	v_mfma_f32_32x32x16_bf16 v[18:33], v[222:225], v[218:221], v[18:33]
	ds_read_b128 v[218:221], v161 offset:23104
	s_waitcnt lgkmcnt(0)
	v_mfma_f32_32x32x16_bf16 v[34:49], v[214:217], v[218:221], v[34:49]
	v_mfma_f32_32x32x16_bf16 v[2:17], v[222:225], v[218:221], v[2:17]
	ds_read_b128 v[214:217], v159 offset:96
	ds_read_b128 v[218:221], v161 offset:18528
	ds_read_b128 v[222:225], v167 offset:4608
	ds_read_b128 v[226:229], v161 offset:23136
	s_waitcnt vmcnt(10)
	s_cmp_eq_u32 s8, 0
	s_cbranch_scc1 .Lc1_skipcb
	s_and_saveexec_b64 s[4:5], s[52:53]
	v_lshlrev_b32_e32 v240, 16, v244
	v_and_b32_e32 v241, 0xffff0000, v244
	v_pk_add_f32 v[240:241], v[248:249], v[240:241]
	s_nop 0
	v_cvt_pk_bf16_f32 v169, v240, v241
	v_lshlrev_b32_e32 v242, 16, v245
	v_and_b32_e32 v243, 0xffff0000, v245
	v_pk_add_f32 v[242:243], v[250:251], v[242:243]
	s_nop 0
	v_cvt_pk_bf16_f32 v67, v242, v243
	v_lshlrev_b32_e32 v240, 16, v246
	v_and_b32_e32 v241, 0xffff0000, v246
	v_pk_add_f32 v[240:241], v[230:231], v[240:241]
	s_nop 0
	v_cvt_pk_bf16_f32 v68, v240, v241
	v_lshlrev_b32_e32 v242, 16, v247
	v_and_b32_e32 v243, 0xffff0000, v247
	v_pk_add_f32 v[242:243], v[190:191], v[242:243]
	s_nop 0
	v_cvt_pk_bf16_f32 v69, v242, v243
	s_or_b64 exec, exec, s[4:5]
	s_and_saveexec_b64 s[4:5], s[56:57]
	v_lshlrev_b32_e32 v240, 16, v78
	v_and_b32_e32 v241, 0xffff0000, v78
	v_pk_add_f32 v[240:241], v[248:249], v[240:241]
	s_nop 0
	v_cvt_pk_bf16_f32 v78, v240, v241
	v_lshlrev_b32_e32 v242, 16, v79
	v_and_b32_e32 v243, 0xffff0000, v79
	v_pk_add_f32 v[242:243], v[250:251], v[242:243]
	s_nop 0
	v_cvt_pk_bf16_f32 v79, v242, v243
	v_lshlrev_b32_e32 v240, 16, v80
	v_and_b32_e32 v241, 0xffff0000, v80
	v_pk_add_f32 v[240:241], v[230:231], v[240:241]
	s_nop 0
	v_cvt_pk_bf16_f32 v80, v240, v241
	v_lshlrev_b32_e32 v242, 16, v81
	v_and_b32_e32 v243, 0xffff0000, v81
	v_pk_add_f32 v[242:243], v[190:191], v[242:243]
	s_nop 0
	v_cvt_pk_bf16_f32 v81, v242, v243
	s_or_b64 exec, exec, s[4:5]
	s_and_saveexec_b64 s[4:5], s[58:59]
	v_lshlrev_b32_e32 v240, 16, v74
	v_and_b32_e32 v241, 0xffff0000, v74
	v_pk_add_f32 v[240:241], v[248:249], v[240:241]
	s_nop 0
	v_cvt_pk_bf16_f32 v74, v240, v241
	v_lshlrev_b32_e32 v242, 16, v75
	v_and_b32_e32 v243, 0xffff0000, v75
	v_pk_add_f32 v[242:243], v[250:251], v[242:243]
	s_nop 0
	v_cvt_pk_bf16_f32 v75, v242, v243
	v_lshlrev_b32_e32 v240, 16, v76
	v_and_b32_e32 v241, 0xffff0000, v76
	v_pk_add_f32 v[240:241], v[230:231], v[240:241]
	s_nop 0
	v_cvt_pk_bf16_f32 v76, v240, v241
	v_lshlrev_b32_e32 v242, 16, v77
	v_and_b32_e32 v243, 0xffff0000, v77
	v_pk_add_f32 v[242:243], v[190:191], v[242:243]
	s_nop 0
	v_cvt_pk_bf16_f32 v77, v242, v243
	s_or_b64 exec, exec, s[4:5]
	s_and_saveexec_b64 s[4:5], s[60:61]
	v_lshlrev_b32_e32 v240, 16, v90
	v_and_b32_e32 v241, 0xffff0000, v90
	v_pk_add_f32 v[240:241], v[248:249], v[240:241]
	s_nop 0
	v_cvt_pk_bf16_f32 v90, v240, v241
	v_lshlrev_b32_e32 v242, 16, v91
	v_and_b32_e32 v243, 0xffff0000, v91
	v_pk_add_f32 v[242:243], v[250:251], v[242:243]
	s_nop 0
	v_cvt_pk_bf16_f32 v91, v242, v243
	v_lshlrev_b32_e32 v240, 16, v92
	v_and_b32_e32 v241, 0xffff0000, v92
	v_pk_add_f32 v[240:241], v[230:231], v[240:241]
	s_nop 0
	v_cvt_pk_bf16_f32 v92, v240, v241
	v_lshlrev_b32_e32 v242, 16, v93
	v_and_b32_e32 v243, 0xffff0000, v93
	v_pk_add_f32 v[242:243], v[190:191], v[242:243]
	s_nop 0
	v_cvt_pk_bf16_f32 v93, v242, v243
	s_or_b64 exec, exec, s[4:5]
	v_mov_b32_e32 v66, v169
.Lc1_skipcb:
	ds_write_b128 v131, v[66:69] offset:36864
	ds_write_b128 v131, v[70:73] offset:55296
	ds_write_b128 v135, v[78:81] offset:36864
	v_lshl_or_b32 v66, s16, 6, v158
	ds_write_b128 v135, v[82:85] offset:55296
	ds_write_b128 v152, v[74:77] offset:36864
	ds_write_b128 v152, v[86:89] offset:55296
	ds_write_b128 v156, v[90:93] offset:36864
	ds_write_b128 v156, v[110:113] offset:55296
	v_lshlrev_b32_e32 v110, 2, v66
	v_mov_b32_e32 v67, 0
	s_waitcnt lgkmcnt(10)
	v_mfma_f32_32x32x16_bf16 v[50:65], v[214:217], v[218:221], v[50:65]
	v_mov_b32_e32 v68, 0
	v_mov_b32_e32 v69, 0
	s_waitcnt lgkmcnt(0)
	s_barrier
	v_mfma_f32_32x32x16_bf16 v[18:33], v[222:225], v[218:221], v[18:33]
	v_mfma_f32_32x32x16_bf16 v[34:49], v[214:217], v[226:229], v[34:49]
	v_mfma_f32_32x32x16_bf16 v[2:17], v[222:225], v[226:229], v[2:17]
	global_load_dwordx2 v[230:231], v110, s[40:41] offset:16
	global_load_dwordx2 v[190:191], v110, s[40:41] offset:24
	global_load_dwordx4 v[248:251], v110, s[40:41]
	s_and_saveexec_b64 s[4:5], s[52:53]
	v_lshl_add_u32 v0, s16, 7, v160
	v_lshl_add_u64 v[244:245], v[176:177], 0, v[0:1]
	global_load_dwordx4 v[244:247], v[244:245], off
	s_or_b64 exec, exec, s[4:5]
	v_mov_b32_e32 v78, 0
	v_mov_b32_e32 v79, 0
	v_mov_b32_e32 v80, 0
	v_mov_b32_e32 v81, 0
	s_and_saveexec_b64 s[4:5], s[56:57]
	v_lshl_add_u32 v0, s16, 7, v164
	v_lshl_add_u64 v[76:77], v[178:179], 0, v[0:1]
	global_load_dwordx4 v[78:81], v[76:77], off
	s_or_b64 exec, exec, s[4:5]
	v_mov_b32_e32 v74, 0
	v_mov_b32_e32 v75, 0
	v_mov_b32_e32 v76, 0
	v_mov_b32_e32 v77, 0
	s_and_saveexec_b64 s[4:5], s[58:59]
	v_lshl_add_u32 v0, s16, 7, v168
	v_lshl_add_u64 v[74:75], v[180:181], 0, v[0:1]
	global_load_dwordx4 v[74:77], v[74:75], off
	s_or_b64 exec, exec, s[4:5]
	v_mov_b32_e32 v90, 0
	v_mov_b32_e32 v91, 0
	v_mov_b32_e32 v92, 0
	v_mov_b32_e32 v93, 0
	s_and_saveexec_b64 s[4:5], s[60:61]
	v_lshl_add_u32 v0, s16, 7, v172
	v_lshl_add_u64 v[90:91], v[182:183], 0, v[0:1]
	global_load_dwordx4 v[90:93], v[90:91], off
	s_or_b64 exec, exec, s[4:5]
	v_add_u32_e32 v0, v66, v162
	v_lshl_add_u64 v[70:71], v[0:1], 1, s[54:55]
	global_load_dwordx4 v[70:73], v[70:71], off
	v_add_u32_e32 v0, v66, v166
	v_lshl_add_u64 v[82:83], v[0:1], 1, s[54:55]
	global_load_dwordx4 v[82:85], v[82:83], off
	v_add_u32_e32 v0, v66, v170
	v_lshl_add_u64 v[86:87], v[0:1], 1, s[54:55]
	global_load_dwordx4 v[86:89], v[86:87], off
	ds_read_b128 v[110:113], v159 offset:36864
	ds_read_b128 v[214:217], v161 offset:55296
	ds_read_b128 v[218:221], v159 offset:41472
	v_add_u32_e32 v0, v66, v174
	v_lshl_add_u64 v[222:223], v[0:1], 1, s[54:55]
	s_cmp_gt_u32 s8, 29
	s_waitcnt lgkmcnt(1)
	v_mfma_f32_32x32x16_bf16 v[50:65], v[110:113], v[214:217], v[50:65]
	s_cselect_b64 s[4:5], -1, 0
	s_and_b64 vcc, exec, s[4:5]
	s_waitcnt lgkmcnt(0)
	v_mfma_f32_32x32x16_bf16 v[18:33], v[218:221], v[214:217], v[18:33]
	ds_read_b128 v[214:217], v161 offset:59904
	s_waitcnt lgkmcnt(0)
	v_mfma_f32_32x32x16_bf16 v[34:49], v[110:113], v[214:217], v[34:49]
	v_mfma_f32_32x32x16_bf16 v[2:17], v[218:221], v[214:217], v[2:17]
	ds_read_b128 v[110:113], v159 offset:36896
	ds_read_b128 v[214:217], v161 offset:55328
	ds_read_b128 v[218:221], v163 offset:41472
	s_waitcnt lgkmcnt(1)
	v_mfma_f32_32x32x16_bf16 v[50:65], v[110:113], v[214:217], v[50:65]
	s_waitcnt lgkmcnt(0)
	v_mfma_f32_32x32x16_bf16 v[18:33], v[218:221], v[214:217], v[18:33]
	ds_read_b128 v[214:217], v161 offset:59936
	s_waitcnt lgkmcnt(0)
	v_mfma_f32_32x32x16_bf16 v[34:49], v[110:113], v[214:217], v[34:49]
	v_mfma_f32_32x32x16_bf16 v[2:17], v[218:221], v[214:217], v[2:17]
	ds_read_b128 v[110:113], v159 offset:36928
	ds_read_b128 v[214:217], v161 offset:55360
	ds_read_b128 v[218:221], v165 offset:41472
	s_waitcnt lgkmcnt(1)
	v_mfma_f32_32x32x16_bf16 v[50:65], v[110:113], v[214:217], v[50:65]
	s_waitcnt lgkmcnt(0)
	v_mfma_f32_32x32x16_bf16 v[18:33], v[218:221], v[214:217], v[18:33]
	ds_read_b128 v[214:217], v161 offset:59968
	s_waitcnt lgkmcnt(0)
	v_mfma_f32_32x32x16_bf16 v[34:49], v[110:113], v[214:217], v[34:49]
	v_mfma_f32_32x32x16_bf16 v[2:17], v[218:221], v[214:217], v[2:17]
	ds_read_b128 v[110:113], v159 offset:36960
	ds_read_b128 v[214:217], v161 offset:55392
	ds_read_b128 v[218:221], v167 offset:41472
	s_waitcnt lgkmcnt(1)
	v_mfma_f32_32x32x16_bf16 v[50:65], v[110:113], v[214:217], v[50:65]
	s_waitcnt lgkmcnt(0)
	v_mfma_f32_32x32x16_bf16 v[18:33], v[218:221], v[214:217], v[18:33]
	ds_read_b128 v[214:217], v161 offset:60000
	s_waitcnt lgkmcnt(0)
	v_mfma_f32_32x32x16_bf16 v[34:49], v[110:113], v[214:217], v[34:49]
	global_load_dwordx4 v[110:113], v[222:223], off
	v_mfma_f32_32x32x16_bf16 v[2:17], v[218:221], v[214:217], v[2:17]
	s_cbranch_vccnz .LBB0_434
	s_waitcnt vmcnt(11)
	s_and_saveexec_b64 s[4:5], s[52:53]
	v_lshlrev_b32_e32 v240, 16, v94
	v_and_b32_e32 v241, 0xffff0000, v94
	v_pk_add_f32 v[240:241], v[232:233], v[240:241]
	s_nop 0
	v_cvt_pk_bf16_f32 v94, v240, v241
	v_lshlrev_b32_e32 v242, 16, v95
	v_and_b32_e32 v243, 0xffff0000, v95
	v_pk_add_f32 v[242:243], v[234:235], v[242:243]
	s_nop 0
	v_cvt_pk_bf16_f32 v95, v242, v243
	v_lshlrev_b32_e32 v240, 16, v96
	v_and_b32_e32 v241, 0xffff0000, v96
	v_pk_add_f32 v[240:241], v[236:237], v[240:241]
	s_nop 0
	v_cvt_pk_bf16_f32 v96, v240, v241
	v_lshlrev_b32_e32 v242, 16, v97
	v_and_b32_e32 v243, 0xffff0000, v97
	v_pk_add_f32 v[242:243], v[238:239], v[242:243]
	s_nop 0
	v_cvt_pk_bf16_f32 v97, v242, v243
	s_or_b64 exec, exec, s[4:5]
	s_and_saveexec_b64 s[4:5], s[56:57]
	v_lshlrev_b32_e32 v240, 16, v106
	v_and_b32_e32 v241, 0xffff0000, v106
	v_pk_add_f32 v[240:241], v[232:233], v[240:241]
	s_nop 0
	v_cvt_pk_bf16_f32 v106, v240, v241
	v_lshlrev_b32_e32 v242, 16, v107
	v_and_b32_e32 v243, 0xffff0000, v107
	v_pk_add_f32 v[242:243], v[234:235], v[242:243]
	s_nop 0
	v_cvt_pk_bf16_f32 v107, v242, v243
	v_lshlrev_b32_e32 v240, 16, v108
	v_and_b32_e32 v241, 0xffff0000, v108
	v_pk_add_f32 v[240:241], v[236:237], v[240:241]
	s_nop 0
	v_cvt_pk_bf16_f32 v108, v240, v241
	v_lshlrev_b32_e32 v242, 16, v109
	v_and_b32_e32 v243, 0xffff0000, v109
	v_pk_add_f32 v[242:243], v[238:239], v[242:243]
	s_nop 0
	v_cvt_pk_bf16_f32 v109, v242, v243
	s_or_b64 exec, exec, s[4:5]
	s_and_saveexec_b64 s[4:5], s[58:59]
	v_lshlrev_b32_e32 v240, 16, v102
	v_and_b32_e32 v241, 0xffff0000, v102
	v_pk_add_f32 v[240:241], v[232:233], v[240:241]
	s_nop 0
	v_cvt_pk_bf16_f32 v102, v240, v241
	v_lshlrev_b32_e32 v242, 16, v103
	v_and_b32_e32 v243, 0xffff0000, v103
	v_pk_add_f32 v[242:243], v[234:235], v[242:243]
	s_nop 0
	v_cvt_pk_bf16_f32 v103, v242, v243
	v_lshlrev_b32_e32 v240, 16, v104
	v_and_b32_e32 v241, 0xffff0000, v104
	v_pk_add_f32 v[240:241], v[236:237], v[240:241]
	s_nop 0
	v_cvt_pk_bf16_f32 v104, v240, v241
	v_lshlrev_b32_e32 v242, 16, v105
	v_and_b32_e32 v243, 0xffff0000, v105
	v_pk_add_f32 v[242:243], v[238:239], v[242:243]
	s_nop 0
	v_cvt_pk_bf16_f32 v105, v242, v243
	s_or_b64 exec, exec, s[4:5]
	s_and_saveexec_b64 s[4:5], s[60:61]
	v_lshlrev_b32_e32 v240, 16, v122
	v_and_b32_e32 v241, 0xffff0000, v122
	v_pk_add_f32 v[240:241], v[232:233], v[240:241]
	s_nop 0
	v_cvt_pk_bf16_f32 v122, v240, v241
	v_lshlrev_b32_e32 v242, 16, v123
	v_and_b32_e32 v243, 0xffff0000, v123
	v_pk_add_f32 v[242:243], v[234:235], v[242:243]
	s_nop 0
	v_cvt_pk_bf16_f32 v123, v242, v243
	v_lshlrev_b32_e32 v240, 16, v124
	v_and_b32_e32 v241, 0xffff0000, v124
	v_pk_add_f32 v[240:241], v[236:237], v[240:241]
	s_nop 0
	v_cvt_pk_bf16_f32 v124, v240, v241
	v_lshlrev_b32_e32 v242, 16, v125
	v_and_b32_e32 v243, 0xffff0000, v125
	v_pk_add_f32 v[242:243], v[238:239], v[242:243]
	s_nop 0
	v_cvt_pk_bf16_f32 v125, v242, v243
	s_or_b64 exec, exec, s[4:5]
	s_mov_b64 s[4:5], 0
	ds_write_b128 v131, v[94:97]
	ds_write_b128 v131, v[98:101] offset:18432
	ds_write_b128 v135, v[106:109]
	ds_write_b128 v135, v[114:117] offset:18432
	ds_write_b128 v152, v[102:105]
	ds_write_b128 v152, v[118:121] offset:18432
	ds_write_b128 v156, v[122:125]
	ds_write_b128 v156, v[126:129] offset:18432
	s_branch .LBB0_434
.LBB0_453:
	s_waitcnt vmcnt(0)
	v_mul_f32_e32 v68, 0xbfb8aa3b, v50
	s_waitcnt vmcnt(3)
	v_exp_f32_e32 v70, v68
	v_mov_b32_e32 v0, v133
	v_mov_b32_e32 v66, v133
	v_add_f32_e32 v70, 1.0, v70
	v_and_b32_e32 v67, 64, v66
	v_and_b32_e32 v69, 31, v0
	v_ashrrev_i32_e32 v66, 1, v66
	v_lshrrev_b32_e32 v0, 3, v0
	v_and_b32_e32 v66, 0xffffffc0, v66
	v_and_or_b32 v0, v0, 4, s6
	s_and_b64 s[4:5], s[38:39], exec
	v_add_u32_e32 v68, v0, v66
	v_or3_b32 v0, v69, v67, s7
	v_div_scale_f32 v71, s[6:7], v70, v70, v50
	s_mov_b32 s4, 0x1ee00000
	v_rcp_f32_e32 v72, v71
	s_cselect_b32 s4, s4, 0x1f000000
	s_add_u32 s4, s92, s4
	s_addc_u32 s5, s93, 0
	v_lshlrev_b32_e32 v0, 1, v0
	v_lshl_add_u64 v[66:67], s[4:5], 0, v[0:1]
	v_fma_f32 v0, -v71, v72, 1.0
	v_fmac_f32_e32 v72, v0, v72
	v_div_scale_f32 v0, vcc, v50, v70, v50
	v_mul_f32_e32 v73, v0, v72
	v_fma_f32 v74, -v71, v73, v0
	v_fmac_f32_e32 v73, v74, v72
	v_fma_f32 v0, -v71, v73, v0
	v_mul_f32_e32 v71, 0xbfb8aa3b, v34
	v_exp_f32_e32 v71, v71
	v_div_fmas_f32 v0, v0, v72, v73
	v_div_fixup_f32 v0, v0, v70, v50
	v_ashrrev_i32_e32 v69, 31, v68
	v_add_f32_e32 v50, 1.0, v71
	v_div_scale_f32 v72, s[4:5], v50, v50, v34
	v_rcp_f32_e32 v73, v72
	v_lshlrev_b64 v[70:71], 9, v[68:69]
	v_cvt_pk_bf16_f32 v0, v0, s0
	v_lshl_add_u64 v[70:71], v[66:67], 0, v[70:71]
	global_store_short v[70:71], v0, off
	v_fma_f32 v0, -v72, v73, 1.0
	v_fmac_f32_e32 v73, v0, v73
	v_div_scale_f32 v0, vcc, v34, v50, v34
	v_mul_f32_e32 v69, v0, v73
	v_fma_f32 v74, -v72, v69, v0
	v_fmac_f32_e32 v69, v74, v73
	v_fma_f32 v0, -v72, v69, v0
	v_mul_f32_e32 v72, 0xbfb8aa3b, v51
	v_exp_f32_e32 v72, v72
	v_div_fmas_f32 v0, v0, v73, v69
	v_div_fixup_f32 v0, v0, v50, v34
	v_cvt_pk_bf16_f32 v0, v0, s0
	v_add_f32_e32 v34, 1.0, v72
	v_div_scale_f32 v50, s[4:5], v34, v34, v51
	v_rcp_f32_e32 v69, v50
	global_store_short v[70:71], v0, off offset:64
	v_or_b32_e32 v70, 1, v68
	v_ashrrev_i32_e32 v71, 31, v70
	v_fma_f32 v0, -v50, v69, 1.0
	v_fmac_f32_e32 v69, v0, v69
	v_div_scale_f32 v0, vcc, v51, v34, v51
	v_mul_f32_e32 v72, v0, v69
	v_fma_f32 v73, -v50, v72, v0
	v_fmac_f32_e32 v72, v73, v69
	v_fma_f32 v0, -v50, v72, v0
	v_mul_f32_e32 v50, 0xbfb8aa3b, v35
	v_exp_f32_e32 v50, v50
	v_div_fmas_f32 v0, v0, v69, v72
	v_div_fixup_f32 v0, v0, v34, v51
	v_cvt_pk_bf16_f32 v0, v0, s0
	v_add_f32_e32 v34, 1.0, v50
	v_div_scale_f32 v69, s[4:5], v34, v34, v35
	v_rcp_f32_e32 v72, v69
	v_lshlrev_b64 v[50:51], 9, v[70:71]
	v_lshl_add_u64 v[50:51], v[66:67], 0, v[50:51]
	global_store_short v[50:51], v0, off
	v_fma_f32 v0, -v69, v72, 1.0
	v_fmac_f32_e32 v72, v0, v72
	v_div_scale_f32 v0, vcc, v35, v34, v35
	v_mul_f32_e32 v70, v0, v72
	v_fma_f32 v71, -v69, v70, v0
	v_fmac_f32_e32 v70, v71, v72
	v_fma_f32 v0, -v69, v70, v0
	v_mul_f32_e32 v69, 0xbfb8aa3b, v52
	v_exp_f32_e32 v69, v69
	v_div_fmas_f32 v0, v0, v72, v70
	v_div_fixup_f32 v0, v0, v34, v35
	v_cvt_pk_bf16_f32 v0, v0, s0
	v_add_f32_e32 v69, 1.0, v69
	v_div_scale_f32 v70, s[4:5], v69, v69, v52
	v_rcp_f32_e32 v71, v70
	global_store_short v[50:51], v0, off offset:64
	v_or_b32_e32 v34, 2, v68
	v_ashrrev_i32_e32 v35, 31, v34
	v_fma_f32 v0, -v70, v71, 1.0
	v_fmac_f32_e32 v71, v0, v71
	v_div_scale_f32 v0, vcc, v52, v69, v52
	v_mul_f32_e32 v50, v0, v71
	v_fma_f32 v51, -v70, v50, v0
	v_fmac_f32_e32 v50, v51, v71
	v_mul_f32_e32 v51, 0xbfb8aa3b, v36
	v_exp_f32_e32 v51, v51
	v_fma_f32 v0, -v70, v50, v0
	v_div_fmas_f32 v0, v0, v71, v50
	v_div_fixup_f32 v0, v0, v69, v52
	v_add_f32_e32 v50, 1.0, v51
	v_div_scale_f32 v51, s[4:5], v50, v50, v36
	v_rcp_f32_e32 v52, v51
	v_lshlrev_b64 v[34:35], 9, v[34:35]
	v_cvt_pk_bf16_f32 v0, v0, s0
	v_lshl_add_u64 v[34:35], v[66:67], 0, v[34:35]
	global_store_short v[34:35], v0, off
	v_fma_f32 v0, -v51, v52, 1.0
	v_fmac_f32_e32 v52, v0, v52
	v_div_scale_f32 v0, vcc, v36, v50, v36
	v_mul_f32_e32 v69, v0, v52
	v_fma_f32 v70, -v51, v69, v0
	v_fmac_f32_e32 v69, v70, v52
	v_fma_f32 v0, -v51, v69, v0
	v_mul_f32_e32 v51, 0xbfb8aa3b, v53
	v_exp_f32_e32 v51, v51
	v_div_fmas_f32 v0, v0, v52, v69
	v_div_fixup_f32 v0, v0, v50, v36
	v_cvt_pk_bf16_f32 v0, v0, s0
	v_add_f32_e32 v36, 1.0, v51
	v_div_scale_f32 v50, s[4:5], v36, v36, v53
	v_rcp_f32_e32 v51, v50
	global_store_short v[34:35], v0, off offset:64
	v_or_b32_e32 v34, 3, v68
	v_ashrrev_i32_e32 v35, 31, v34
	v_fma_f32 v0, -v50, v51, 1.0
	v_fmac_f32_e32 v51, v0, v51
	v_div_scale_f32 v0, vcc, v53, v36, v53
	v_mul_f32_e32 v52, v0, v51
	v_fma_f32 v69, -v50, v52, v0
	v_fmac_f32_e32 v52, v69, v51
	v_fma_f32 v0, -v50, v52, v0
	v_mul_f32_e32 v50, 0xbfb8aa3b, v37
	v_exp_f32_e32 v50, v50
	v_div_fmas_f32 v0, v0, v51, v52
	v_div_fixup_f32 v0, v0, v36, v53
	v_lshlrev_b64 v[34:35], 9, v[34:35]
	v_add_f32_e32 v36, 1.0, v50
	v_div_scale_f32 v50, s[4:5], v36, v36, v37
	v_rcp_f32_e32 v51, v50
	v_cvt_pk_bf16_f32 v0, v0, s0
	v_lshl_add_u64 v[34:35], v[66:67], 0, v[34:35]
	global_store_short v[34:35], v0, off
	v_fma_f32 v0, -v50, v51, 1.0
	v_fmac_f32_e32 v51, v0, v51
	v_div_scale_f32 v0, vcc, v37, v36, v37
	v_mul_f32_e32 v52, v0, v51
	v_fma_f32 v53, -v50, v52, v0
	v_fmac_f32_e32 v52, v53, v51
	v_fma_f32 v0, -v50, v52, v0
	v_mul_f32_e32 v50, 0xbfb8aa3b, v54
	v_exp_f32_e32 v50, v50
	v_div_fmas_f32 v0, v0, v51, v52
	v_div_fixup_f32 v0, v0, v36, v37
	v_cvt_pk_bf16_f32 v0, v0, s0
	v_add_f32_e32 v36, 1.0, v50
	v_div_scale_f32 v37, s[4:5], v36, v36, v54
	v_rcp_f32_e32 v50, v37
	global_store_short v[34:35], v0, off offset:64
	v_or_b32_e32 v34, 8, v68
	v_ashrrev_i32_e32 v35, 31, v34
	v_fma_f32 v0, -v37, v50, 1.0
	v_fmac_f32_e32 v50, v0, v50
	v_div_scale_f32 v0, vcc, v54, v36, v54
	v_mul_f32_e32 v51, v0, v50
	v_fma_f32 v52, -v37, v51, v0
	v_fmac_f32_e32 v51, v52, v50
	v_fma_f32 v0, -v37, v51, v0
	v_mul_f32_e32 v37, 0xbfb8aa3b, v38
	v_exp_f32_e32 v37, v37
	v_div_fmas_f32 v0, v0, v50, v51
	v_div_fixup_f32 v0, v0, v36, v54
	v_lshlrev_b64 v[34:35], 9, v[34:35]
	v_add_f32_e32 v36, 1.0, v37
	v_div_scale_f32 v37, s[4:5], v36, v36, v38
	v_rcp_f32_e32 v50, v37
	v_cvt_pk_bf16_f32 v0, v0, s0
	v_lshl_add_u64 v[34:35], v[66:67], 0, v[34:35]
	global_store_short v[34:35], v0, off
	v_fma_f32 v0, -v37, v50, 1.0
	v_fmac_f32_e32 v50, v0, v50
	v_div_scale_f32 v0, vcc, v38, v36, v38
	v_mul_f32_e32 v51, v0, v50
	v_fma_f32 v52, -v37, v51, v0
	v_fmac_f32_e32 v51, v52, v50
	v_fma_f32 v0, -v37, v51, v0
	v_mul_f32_e32 v37, 0xbfb8aa3b, v55
	v_exp_f32_e32 v37, v37
	v_div_fmas_f32 v0, v0, v50, v51
	v_div_fixup_f32 v0, v0, v36, v38
	v_cvt_pk_bf16_f32 v0, v0, s0
	v_add_f32_e32 v36, 1.0, v37
	v_div_scale_f32 v37, s[4:5], v36, v36, v55
	v_rcp_f32_e32 v38, v37
	global_store_short v[34:35], v0, off offset:64
	v_or_b32_e32 v34, 9, v68
	v_ashrrev_i32_e32 v35, 31, v34
	v_fma_f32 v0, -v37, v38, 1.0
	v_fmac_f32_e32 v38, v0, v38
	v_div_scale_f32 v0, vcc, v55, v36, v55
	v_mul_f32_e32 v50, v0, v38
	v_fma_f32 v51, -v37, v50, v0
	v_fmac_f32_e32 v50, v51, v38
	v_fma_f32 v0, -v37, v50, v0
	v_mul_f32_e32 v37, 0xbfb8aa3b, v39
	v_exp_f32_e32 v37, v37
	v_div_fmas_f32 v0, v0, v38, v50
	v_div_fixup_f32 v0, v0, v36, v55
	v_lshlrev_b64 v[34:35], 9, v[34:35]
	v_add_f32_e32 v36, 1.0, v37
	v_div_scale_f32 v37, s[4:5], v36, v36, v39
	v_rcp_f32_e32 v38, v37
	v_cvt_pk_bf16_f32 v0, v0, s0
	v_lshl_add_u64 v[34:35], v[66:67], 0, v[34:35]
	global_store_short v[34:35], v0, off
	v_fma_f32 v0, -v37, v38, 1.0
	v_fmac_f32_e32 v38, v0, v38
	v_div_scale_f32 v0, vcc, v39, v36, v39
	v_mul_f32_e32 v50, v0, v38
	v_fma_f32 v51, -v37, v50, v0
	v_fmac_f32_e32 v50, v51, v38
	v_fma_f32 v0, -v37, v50, v0
	v_mul_f32_e32 v37, 0xbfb8aa3b, v56
	v_exp_f32_e32 v37, v37
	v_div_fmas_f32 v0, v0, v38, v50
	v_div_fixup_f32 v0, v0, v36, v39
	v_cvt_pk_bf16_f32 v0, v0, s0
	v_add_f32_e32 v36, 1.0, v37
	v_div_scale_f32 v37, s[4:5], v36, v36, v56
	v_rcp_f32_e32 v38, v37
	global_store_short v[34:35], v0, off offset:64
	v_or_b32_e32 v34, 10, v68
	v_ashrrev_i32_e32 v35, 31, v34
	v_fma_f32 v0, -v37, v38, 1.0
	v_fmac_f32_e32 v38, v0, v38
	v_div_scale_f32 v0, vcc, v56, v36, v56
	v_mul_f32_e32 v39, v0, v38
	v_fma_f32 v50, -v37, v39, v0
	v_fmac_f32_e32 v39, v50, v38
	v_fma_f32 v0, -v37, v39, v0
	v_mul_f32_e32 v37, 0xbfb8aa3b, v40
	v_exp_f32_e32 v37, v37
	v_div_fmas_f32 v0, v0, v38, v39
	v_div_fixup_f32 v0, v0, v36, v56
	v_lshlrev_b64 v[34:35], 9, v[34:35]
	v_add_f32_e32 v36, 1.0, v37
	v_div_scale_f32 v37, s[4:5], v36, v36, v40
	v_rcp_f32_e32 v38, v37
	v_cvt_pk_bf16_f32 v0, v0, s0
	v_lshl_add_u64 v[34:35], v[66:67], 0, v[34:35]
	global_store_short v[34:35], v0, off
	v_fma_f32 v0, -v37, v38, 1.0
	v_fmac_f32_e32 v38, v0, v38
	v_div_scale_f32 v0, vcc, v40, v36, v40
	v_mul_f32_e32 v39, v0, v38
	v_fma_f32 v50, -v37, v39, v0
	v_fmac_f32_e32 v39, v50, v38
	v_fma_f32 v0, -v37, v39, v0
	v_mul_f32_e32 v37, 0xbfb8aa3b, v57
	v_exp_f32_e32 v37, v37
	v_div_fmas_f32 v0, v0, v38, v39
	v_div_fixup_f32 v0, v0, v36, v40
	v_cvt_pk_bf16_f32 v0, v0, s0
	v_add_f32_e32 v36, 1.0, v37
	v_div_scale_f32 v37, s[4:5], v36, v36, v57
	v_rcp_f32_e32 v38, v37
	global_store_short v[34:35], v0, off offset:64
	v_or_b32_e32 v34, 11, v68
	v_ashrrev_i32_e32 v35, 31, v34
	v_fma_f32 v0, -v37, v38, 1.0
	v_fmac_f32_e32 v38, v0, v38
	v_div_scale_f32 v0, vcc, v57, v36, v57
	v_mul_f32_e32 v39, v0, v38
	v_fma_f32 v40, -v37, v39, v0
	v_fmac_f32_e32 v39, v40, v38
	v_fma_f32 v0, -v37, v39, v0
	v_mul_f32_e32 v37, 0xbfb8aa3b, v41
	v_exp_f32_e32 v37, v37
	v_div_fmas_f32 v0, v0, v38, v39
	v_div_fixup_f32 v0, v0, v36, v57
	v_lshlrev_b64 v[34:35], 9, v[34:35]
	v_add_f32_e32 v36, 1.0, v37
	v_div_scale_f32 v37, s[4:5], v36, v36, v41
	v_rcp_f32_e32 v38, v37
	v_cvt_pk_bf16_f32 v0, v0, s0
	v_lshl_add_u64 v[34:35], v[66:67], 0, v[34:35]
	global_store_short v[34:35], v0, off
	v_fma_f32 v0, -v37, v38, 1.0
	v_fmac_f32_e32 v38, v0, v38
	v_div_scale_f32 v0, vcc, v41, v36, v41
	v_mul_f32_e32 v39, v0, v38
	v_fma_f32 v40, -v37, v39, v0
	v_fmac_f32_e32 v39, v40, v38
	v_fma_f32 v0, -v37, v39, v0
	v_mul_f32_e32 v37, 0xbfb8aa3b, v58
	v_exp_f32_e32 v37, v37
	v_div_fmas_f32 v0, v0, v38, v39
	v_div_fixup_f32 v0, v0, v36, v41
	v_cvt_pk_bf16_f32 v0, v0, s0
	v_add_f32_e32 v36, 1.0, v37
	v_div_scale_f32 v37, s[4:5], v36, v36, v58
	v_rcp_f32_e32 v38, v37
	global_store_short v[34:35], v0, off offset:64
	v_or_b32_e32 v34, 16, v68
	v_ashrrev_i32_e32 v35, 31, v34
	v_fma_f32 v0, -v37, v38, 1.0
	v_fmac_f32_e32 v38, v0, v38
	v_div_scale_f32 v0, vcc, v58, v36, v58
	v_mul_f32_e32 v39, v0, v38
	v_fma_f32 v40, -v37, v39, v0
	v_fmac_f32_e32 v39, v40, v38
	v_fma_f32 v0, -v37, v39, v0
	v_mul_f32_e32 v37, 0xbfb8aa3b, v42
	v_exp_f32_e32 v37, v37
	v_div_fmas_f32 v0, v0, v38, v39
	v_div_fixup_f32 v0, v0, v36, v58
	v_lshlrev_b64 v[34:35], 9, v[34:35]
	v_add_f32_e32 v36, 1.0, v37
	v_div_scale_f32 v37, s[4:5], v36, v36, v42
	v_rcp_f32_e32 v38, v37
	v_cvt_pk_bf16_f32 v0, v0, s0
	v_lshl_add_u64 v[34:35], v[66:67], 0, v[34:35]
	global_store_short v[34:35], v0, off
	v_fma_f32 v0, -v37, v38, 1.0
	v_fmac_f32_e32 v38, v0, v38
	v_div_scale_f32 v0, vcc, v42, v36, v42
	v_mul_f32_e32 v39, v0, v38
	v_fma_f32 v40, -v37, v39, v0
	v_fmac_f32_e32 v39, v40, v38
	v_fma_f32 v0, -v37, v39, v0
	v_mul_f32_e32 v37, 0xbfb8aa3b, v59
	v_exp_f32_e32 v37, v37
	v_div_fmas_f32 v0, v0, v38, v39
	v_div_fixup_f32 v0, v0, v36, v42
	v_cvt_pk_bf16_f32 v0, v0, s0
	v_add_f32_e32 v36, 1.0, v37
	v_div_scale_f32 v37, s[4:5], v36, v36, v59
	v_rcp_f32_e32 v38, v37
	global_store_short v[34:35], v0, off offset:64
	v_or_b32_e32 v34, 17, v68
	v_ashrrev_i32_e32 v35, 31, v34
	v_fma_f32 v0, -v37, v38, 1.0
	v_fmac_f32_e32 v38, v0, v38
	v_div_scale_f32 v0, vcc, v59, v36, v59
	v_mul_f32_e32 v39, v0, v38
	v_fma_f32 v40, -v37, v39, v0
	v_fmac_f32_e32 v39, v40, v38
	v_fma_f32 v0, -v37, v39, v0
	v_mul_f32_e32 v37, 0xbfb8aa3b, v43
	v_exp_f32_e32 v37, v37
	v_div_fmas_f32 v0, v0, v38, v39
	v_div_fixup_f32 v0, v0, v36, v59
	v_lshlrev_b64 v[34:35], 9, v[34:35]
	v_add_f32_e32 v36, 1.0, v37
	v_div_scale_f32 v37, s[4:5], v36, v36, v43
	v_rcp_f32_e32 v38, v37
	v_cvt_pk_bf16_f32 v0, v0, s0
	v_lshl_add_u64 v[34:35], v[66:67], 0, v[34:35]
	global_store_short v[34:35], v0, off
	v_fma_f32 v0, -v37, v38, 1.0
	v_fmac_f32_e32 v38, v0, v38
	v_div_scale_f32 v0, vcc, v43, v36, v43
	v_mul_f32_e32 v39, v0, v38
	v_fma_f32 v40, -v37, v39, v0
	v_fmac_f32_e32 v39, v40, v38
	v_fma_f32 v0, -v37, v39, v0
	v_mul_f32_e32 v37, 0xbfb8aa3b, v60
	v_exp_f32_e32 v37, v37
	v_div_fmas_f32 v0, v0, v38, v39
	v_div_fixup_f32 v0, v0, v36, v43
	v_cvt_pk_bf16_f32 v0, v0, s0
	v_add_f32_e32 v36, 1.0, v37
	v_div_scale_f32 v37, s[4:5], v36, v36, v60
	v_rcp_f32_e32 v38, v37
	global_store_short v[34:35], v0, off offset:64
	v_or_b32_e32 v34, 18, v68
	v_ashrrev_i32_e32 v35, 31, v34
	v_fma_f32 v0, -v37, v38, 1.0
	v_fmac_f32_e32 v38, v0, v38
	v_div_scale_f32 v0, vcc, v60, v36, v60
	v_mul_f32_e32 v39, v0, v38
	v_fma_f32 v40, -v37, v39, v0
	v_fmac_f32_e32 v39, v40, v38
	v_fma_f32 v0, -v37, v39, v0
	v_mul_f32_e32 v37, 0xbfb8aa3b, v44
	v_exp_f32_e32 v37, v37
	v_div_fmas_f32 v0, v0, v38, v39
	v_div_fixup_f32 v0, v0, v36, v60
	v_lshlrev_b64 v[34:35], 9, v[34:35]
	v_add_f32_e32 v36, 1.0, v37
	v_div_scale_f32 v37, s[4:5], v36, v36, v44
	v_rcp_f32_e32 v38, v37
	v_cvt_pk_bf16_f32 v0, v0, s0
	v_lshl_add_u64 v[34:35], v[66:67], 0, v[34:35]
	global_store_short v[34:35], v0, off
	v_fma_f32 v0, -v37, v38, 1.0
	v_fmac_f32_e32 v38, v0, v38
	v_div_scale_f32 v0, vcc, v44, v36, v44
	v_mul_f32_e32 v39, v0, v38
	v_fma_f32 v40, -v37, v39, v0
	v_fmac_f32_e32 v39, v40, v38
	v_fma_f32 v0, -v37, v39, v0
	v_mul_f32_e32 v37, 0xbfb8aa3b, v61
	v_exp_f32_e32 v37, v37
	v_div_fmas_f32 v0, v0, v38, v39
	v_div_fixup_f32 v0, v0, v36, v44
	v_cvt_pk_bf16_f32 v0, v0, s0
	v_add_f32_e32 v36, 1.0, v37
	v_div_scale_f32 v37, s[4:5], v36, v36, v61
	v_rcp_f32_e32 v38, v37
	global_store_short v[34:35], v0, off offset:64
	v_or_b32_e32 v34, 19, v68
	v_ashrrev_i32_e32 v35, 31, v34
	v_fma_f32 v0, -v37, v38, 1.0
	v_fmac_f32_e32 v38, v0, v38
	v_div_scale_f32 v0, vcc, v61, v36, v61
	v_mul_f32_e32 v39, v0, v38
	v_fma_f32 v40, -v37, v39, v0
	v_fmac_f32_e32 v39, v40, v38
	v_fma_f32 v0, -v37, v39, v0
	v_mul_f32_e32 v37, 0xbfb8aa3b, v45
	v_exp_f32_e32 v37, v37
	v_div_fmas_f32 v0, v0, v38, v39
	v_div_fixup_f32 v0, v0, v36, v61
	v_lshlrev_b64 v[34:35], 9, v[34:35]
	v_add_f32_e32 v36, 1.0, v37
	v_div_scale_f32 v37, s[4:5], v36, v36, v45
	v_rcp_f32_e32 v38, v37
	v_cvt_pk_bf16_f32 v0, v0, s0
	v_lshl_add_u64 v[34:35], v[66:67], 0, v[34:35]
	global_store_short v[34:35], v0, off
	v_fma_f32 v0, -v37, v38, 1.0
	v_fmac_f32_e32 v38, v0, v38
	v_div_scale_f32 v0, vcc, v45, v36, v45
	v_mul_f32_e32 v39, v0, v38
	v_fma_f32 v40, -v37, v39, v0
	v_fmac_f32_e32 v39, v40, v38
	v_fma_f32 v0, -v37, v39, v0
	v_mul_f32_e32 v37, 0xbfb8aa3b, v62
	v_exp_f32_e32 v37, v37
	v_div_fmas_f32 v0, v0, v38, v39
	v_div_fixup_f32 v0, v0, v36, v45
	v_cvt_pk_bf16_f32 v0, v0, s0
	v_add_f32_e32 v36, 1.0, v37
	v_div_scale_f32 v37, s[4:5], v36, v36, v62
	v_rcp_f32_e32 v38, v37
	global_store_short v[34:35], v0, off offset:64
	v_or_b32_e32 v34, 24, v68
	v_ashrrev_i32_e32 v35, 31, v34
	v_fma_f32 v0, -v37, v38, 1.0
	v_fmac_f32_e32 v38, v0, v38
	v_div_scale_f32 v0, vcc, v62, v36, v62
	v_mul_f32_e32 v39, v0, v38
	v_fma_f32 v40, -v37, v39, v0
	v_fmac_f32_e32 v39, v40, v38
	v_fma_f32 v0, -v37, v39, v0
	v_mul_f32_e32 v37, 0xbfb8aa3b, v46
	v_exp_f32_e32 v37, v37
	v_div_fmas_f32 v0, v0, v38, v39
	v_div_fixup_f32 v0, v0, v36, v62
	v_lshlrev_b64 v[34:35], 9, v[34:35]
	v_add_f32_e32 v36, 1.0, v37
	v_div_scale_f32 v37, s[4:5], v36, v36, v46
	v_rcp_f32_e32 v38, v37
	v_cvt_pk_bf16_f32 v0, v0, s0
	v_lshl_add_u64 v[34:35], v[66:67], 0, v[34:35]
	global_store_short v[34:35], v0, off
	v_fma_f32 v0, -v37, v38, 1.0
	v_fmac_f32_e32 v38, v0, v38
	v_div_scale_f32 v0, vcc, v46, v36, v46
	v_mul_f32_e32 v39, v0, v38
	v_fma_f32 v40, -v37, v39, v0
	v_fmac_f32_e32 v39, v40, v38
	v_fma_f32 v0, -v37, v39, v0
	v_mul_f32_e32 v37, 0xbfb8aa3b, v63
	v_exp_f32_e32 v37, v37
	v_div_fmas_f32 v0, v0, v38, v39
	v_div_fixup_f32 v0, v0, v36, v46
	v_cvt_pk_bf16_f32 v0, v0, s0
	v_add_f32_e32 v36, 1.0, v37
	v_div_scale_f32 v37, s[4:5], v36, v36, v63
	v_rcp_f32_e32 v38, v37
	global_store_short v[34:35], v0, off offset:64
	v_or_b32_e32 v34, 25, v68
	v_ashrrev_i32_e32 v35, 31, v34
	v_fma_f32 v0, -v37, v38, 1.0
	v_fmac_f32_e32 v38, v0, v38
	v_div_scale_f32 v0, vcc, v63, v36, v63
	v_mul_f32_e32 v39, v0, v38
	v_fma_f32 v40, -v37, v39, v0
	v_fmac_f32_e32 v39, v40, v38
	v_fma_f32 v0, -v37, v39, v0
	v_mul_f32_e32 v37, 0xbfb8aa3b, v47
	v_exp_f32_e32 v37, v37
	v_div_fmas_f32 v0, v0, v38, v39
	v_div_fixup_f32 v0, v0, v36, v63
	v_lshlrev_b64 v[34:35], 9, v[34:35]
	v_add_f32_e32 v36, 1.0, v37
	v_div_scale_f32 v37, s[4:5], v36, v36, v47
	v_rcp_f32_e32 v38, v37
	v_cvt_pk_bf16_f32 v0, v0, s0
	v_lshl_add_u64 v[34:35], v[66:67], 0, v[34:35]
	global_store_short v[34:35], v0, off
	v_fma_f32 v0, -v37, v38, 1.0
	v_fmac_f32_e32 v38, v0, v38
	v_div_scale_f32 v0, vcc, v47, v36, v47
	v_mul_f32_e32 v39, v0, v38
	v_fma_f32 v40, -v37, v39, v0
	v_fmac_f32_e32 v39, v40, v38
	v_fma_f32 v0, -v37, v39, v0
	v_mul_f32_e32 v37, 0xbfb8aa3b, v64
	v_exp_f32_e32 v37, v37
	v_div_fmas_f32 v0, v0, v38, v39
	v_div_fixup_f32 v0, v0, v36, v47
	v_cvt_pk_bf16_f32 v0, v0, s0
	v_add_f32_e32 v36, 1.0, v37
	v_div_scale_f32 v37, s[4:5], v36, v36, v64
	v_rcp_f32_e32 v38, v37
	global_store_short v[34:35], v0, off offset:64
	v_or_b32_e32 v34, 26, v68
	v_ashrrev_i32_e32 v35, 31, v34
	v_fma_f32 v0, -v37, v38, 1.0
	v_fmac_f32_e32 v38, v0, v38
	v_div_scale_f32 v0, vcc, v64, v36, v64
	v_mul_f32_e32 v39, v0, v38
	v_fma_f32 v40, -v37, v39, v0
	v_fmac_f32_e32 v39, v40, v38
	v_fma_f32 v0, -v37, v39, v0
	v_mul_f32_e32 v37, 0xbfb8aa3b, v48
	v_exp_f32_e32 v37, v37
	v_div_fmas_f32 v0, v0, v38, v39
	v_div_fixup_f32 v0, v0, v36, v64
	v_lshlrev_b64 v[34:35], 9, v[34:35]
	v_add_f32_e32 v36, 1.0, v37
	v_div_scale_f32 v37, s[4:5], v36, v36, v48
	v_rcp_f32_e32 v38, v37
	v_cvt_pk_bf16_f32 v0, v0, s0
	v_lshl_add_u64 v[34:35], v[66:67], 0, v[34:35]
	global_store_short v[34:35], v0, off
	v_fma_f32 v0, -v37, v38, 1.0
	v_fmac_f32_e32 v38, v0, v38
	v_div_scale_f32 v0, vcc, v48, v36, v48
	v_mul_f32_e32 v39, v0, v38
	v_fma_f32 v40, -v37, v39, v0
	v_fmac_f32_e32 v39, v40, v38
	v_fma_f32 v0, -v37, v39, v0
	v_mul_f32_e32 v37, 0xbfb8aa3b, v65
	v_exp_f32_e32 v37, v37
	v_div_fmas_f32 v0, v0, v38, v39
	v_div_fixup_f32 v0, v0, v36, v48
	v_cvt_pk_bf16_f32 v0, v0, s0
	v_add_f32_e32 v36, 1.0, v37
	v_div_scale_f32 v37, s[4:5], v36, v36, v65
	v_rcp_f32_e32 v38, v37
	global_store_short v[34:35], v0, off offset:64
	v_or_b32_e32 v34, 27, v68
	v_ashrrev_i32_e32 v35, 31, v34
	v_fma_f32 v0, -v37, v38, 1.0
	v_fmac_f32_e32 v38, v0, v38
	v_div_scale_f32 v0, vcc, v65, v36, v65
	v_mul_f32_e32 v39, v0, v38
	v_fma_f32 v40, -v37, v39, v0
	v_fmac_f32_e32 v39, v40, v38
	v_fma_f32 v0, -v37, v39, v0
	v_mul_f32_e32 v37, 0xbfb8aa3b, v49
	v_exp_f32_e32 v37, v37
	v_div_fmas_f32 v0, v0, v38, v39
	v_div_fixup_f32 v0, v0, v36, v65
	v_lshlrev_b64 v[34:35], 9, v[34:35]
	v_add_f32_e32 v36, 1.0, v37
	v_div_scale_f32 v37, s[4:5], v36, v36, v49
	v_rcp_f32_e32 v38, v37
	v_cvt_pk_bf16_f32 v0, v0, s0
	v_lshl_add_u64 v[34:35], v[66:67], 0, v[34:35]
	global_store_short v[34:35], v0, off
	v_fma_f32 v0, -v37, v38, 1.0
	v_fmac_f32_e32 v38, v0, v38
	v_div_scale_f32 v0, vcc, v49, v36, v49
	v_mul_f32_e32 v39, v0, v38
	v_fma_f32 v40, -v37, v39, v0
	v_fmac_f32_e32 v39, v40, v38
	v_fma_f32 v0, -v37, v39, v0
	v_mul_f32_e32 v37, 0xbfb8aa3b, v18
	v_exp_f32_e32 v37, v37
	v_div_fmas_f32 v0, v0, v38, v39
	v_div_fixup_f32 v0, v0, v36, v49
	v_cvt_pk_bf16_f32 v0, v0, s0
	v_add_f32_e32 v36, 1.0, v37
	v_div_scale_f32 v37, s[4:5], v36, v36, v18
	v_rcp_f32_e32 v38, v37
	global_store_short v[34:35], v0, off offset:64
	v_or_b32_e32 v34, 32, v68
	v_ashrrev_i32_e32 v35, 31, v34
	v_fma_f32 v0, -v37, v38, 1.0
	v_fmac_f32_e32 v38, v0, v38
	v_div_scale_f32 v0, vcc, v18, v36, v18
	v_mul_f32_e32 v39, v0, v38
	v_fma_f32 v40, -v37, v39, v0
	v_fmac_f32_e32 v39, v40, v38
	v_fma_f32 v0, -v37, v39, v0
	v_mul_f32_e32 v37, 0xbfb8aa3b, v2
	v_exp_f32_e32 v37, v37
	v_div_fmas_f32 v0, v0, v38, v39
	v_div_fixup_f32 v0, v0, v36, v18
	v_lshlrev_b64 v[34:35], 9, v[34:35]
	v_add_f32_e32 v18, 1.0, v37
	v_div_scale_f32 v36, s[4:5], v18, v18, v2
	v_rcp_f32_e32 v37, v36
	v_cvt_pk_bf16_f32 v0, v0, s0
	v_lshl_add_u64 v[34:35], v[66:67], 0, v[34:35]
	global_store_short v[34:35], v0, off
	v_fma_f32 v0, -v36, v37, 1.0
	v_fmac_f32_e32 v37, v0, v37
	v_div_scale_f32 v0, vcc, v2, v18, v2
	v_mul_f32_e32 v38, v0, v37
	v_fma_f32 v39, -v36, v38, v0
	v_fmac_f32_e32 v38, v39, v37
	v_fma_f32 v0, -v36, v38, v0
	v_mul_f32_e32 v36, 0xbfb8aa3b, v19
	v_exp_f32_e32 v36, v36
	v_div_fmas_f32 v0, v0, v37, v38
	v_div_fixup_f32 v0, v0, v18, v2
	v_cvt_pk_bf16_f32 v0, v0, s0
	v_add_f32_e32 v2, 1.0, v36
	v_div_scale_f32 v18, s[4:5], v2, v2, v19
	v_rcp_f32_e32 v36, v18
	global_store_short v[34:35], v0, off offset:64
	v_or_b32_e32 v34, 33, v68
	v_ashrrev_i32_e32 v35, 31, v34
	v_fma_f32 v0, -v18, v36, 1.0
	v_fmac_f32_e32 v36, v0, v36
	v_div_scale_f32 v0, vcc, v19, v2, v19
	v_mul_f32_e32 v37, v0, v36
	v_fma_f32 v38, -v18, v37, v0
	v_fmac_f32_e32 v37, v38, v36
	v_fma_f32 v0, -v18, v37, v0
	v_mul_f32_e32 v18, 0xbfb8aa3b, v3
	v_exp_f32_e32 v18, v18
	v_div_fmas_f32 v0, v0, v36, v37
	v_div_fixup_f32 v0, v0, v2, v19
	v_cvt_pk_bf16_f32 v0, v0, s0
	v_add_f32_e32 v2, 1.0, v18
	v_div_scale_f32 v36, s[4:5], v2, v2, v3
	v_rcp_f32_e32 v37, v36
	v_lshlrev_b64 v[18:19], 9, v[34:35]
	v_lshl_add_u64 v[18:19], v[66:67], 0, v[18:19]
	global_store_short v[18:19], v0, off
	v_fma_f32 v0, -v36, v37, 1.0
	v_fmac_f32_e32 v37, v0, v37
	v_div_scale_f32 v0, vcc, v3, v2, v3
	v_mul_f32_e32 v34, v0, v37
	v_fma_f32 v35, -v36, v34, v0
	v_fmac_f32_e32 v34, v35, v37
	v_mul_f32_e32 v35, 0xbfb8aa3b, v20
	v_exp_f32_e32 v35, v35
	v_fma_f32 v0, -v36, v34, v0
	v_div_fmas_f32 v0, v0, v37, v34
	v_div_fixup_f32 v0, v0, v2, v3
	v_add_f32_e32 v34, 1.0, v35
	v_div_scale_f32 v35, s[4:5], v34, v34, v20
	v_rcp_f32_e32 v36, v35
	v_cvt_pk_bf16_f32 v0, v0, s0
	global_store_short v[18:19], v0, off offset:64
	v_or_b32_e32 v2, 34, v68
	v_fma_f32 v0, -v35, v36, 1.0
	v_fmac_f32_e32 v36, v0, v36
	v_div_scale_f32 v0, vcc, v20, v34, v20
	v_mul_f32_e32 v18, v0, v36
	v_fma_f32 v19, -v35, v18, v0
	v_fmac_f32_e32 v18, v19, v36
	v_mul_f32_e32 v19, 0xbfb8aa3b, v4
	v_exp_f32_e32 v19, v19
	v_fma_f32 v0, -v35, v18, v0
	v_div_fmas_f32 v0, v0, v36, v18
	v_div_fixup_f32 v0, v0, v34, v20
	v_add_f32_e32 v18, 1.0, v19
	v_div_scale_f32 v19, s[4:5], v18, v18, v4
	v_rcp_f32_e32 v20, v19
	v_ashrrev_i32_e32 v3, 31, v2
	v_lshlrev_b64 v[2:3], 9, v[2:3]
	v_cvt_pk_bf16_f32 v0, v0, s0
	v_lshl_add_u64 v[2:3], v[66:67], 0, v[2:3]
	global_store_short v[2:3], v0, off
	v_fma_f32 v0, -v19, v20, 1.0
	v_fmac_f32_e32 v20, v0, v20
	v_div_scale_f32 v0, vcc, v4, v18, v4
	v_mul_f32_e32 v34, v0, v20
	v_fma_f32 v35, -v19, v34, v0
	v_fmac_f32_e32 v34, v35, v20
	v_fma_f32 v0, -v19, v34, v0
	v_mul_f32_e32 v19, 0xbfb8aa3b, v21
	v_exp_f32_e32 v19, v19
	v_div_fmas_f32 v0, v0, v20, v34
	v_div_fixup_f32 v0, v0, v18, v4
	v_cvt_pk_bf16_f32 v0, v0, s0
	v_add_f32_e32 v4, 1.0, v19
	v_div_scale_f32 v18, s[4:5], v4, v4, v21
	v_rcp_f32_e32 v19, v18
	global_store_short v[2:3], v0, off offset:64
	v_or_b32_e32 v2, 35, v68
	v_ashrrev_i32_e32 v3, 31, v2
	v_fma_f32 v0, -v18, v19, 1.0
	v_fmac_f32_e32 v19, v0, v19
	v_div_scale_f32 v0, vcc, v21, v4, v21
	v_mul_f32_e32 v20, v0, v19
	v_fma_f32 v34, -v18, v20, v0
	v_fmac_f32_e32 v20, v34, v19
	v_fma_f32 v0, -v18, v20, v0
	v_mul_f32_e32 v18, 0xbfb8aa3b, v5
	v_exp_f32_e32 v18, v18
	v_div_fmas_f32 v0, v0, v19, v20
	v_div_fixup_f32 v0, v0, v4, v21
	v_lshlrev_b64 v[2:3], 9, v[2:3]
	v_add_f32_e32 v4, 1.0, v18
	v_div_scale_f32 v18, s[4:5], v4, v4, v5
	v_rcp_f32_e32 v19, v18
	v_cvt_pk_bf16_f32 v0, v0, s0
	v_lshl_add_u64 v[2:3], v[66:67], 0, v[2:3]
	global_store_short v[2:3], v0, off
	v_fma_f32 v0, -v18, v19, 1.0
	v_fmac_f32_e32 v19, v0, v19
	v_div_scale_f32 v0, vcc, v5, v4, v5
	v_mul_f32_e32 v20, v0, v19
	v_fma_f32 v21, -v18, v20, v0
	v_fmac_f32_e32 v20, v21, v19
	v_fma_f32 v0, -v18, v20, v0
	v_mul_f32_e32 v18, 0xbfb8aa3b, v22
	v_exp_f32_e32 v18, v18
	v_div_fmas_f32 v0, v0, v19, v20
	v_div_fixup_f32 v0, v0, v4, v5
	v_cvt_pk_bf16_f32 v0, v0, s0
	v_add_f32_e32 v4, 1.0, v18
	v_div_scale_f32 v5, s[4:5], v4, v4, v22
	v_rcp_f32_e32 v18, v5
	global_store_short v[2:3], v0, off offset:64
	v_or_b32_e32 v2, 40, v68
	v_ashrrev_i32_e32 v3, 31, v2
	v_fma_f32 v0, -v5, v18, 1.0
	v_fmac_f32_e32 v18, v0, v18
	v_div_scale_f32 v0, vcc, v22, v4, v22
	v_mul_f32_e32 v19, v0, v18
	v_fma_f32 v20, -v5, v19, v0
	v_fmac_f32_e32 v19, v20, v18
	v_fma_f32 v0, -v5, v19, v0
	v_mul_f32_e32 v5, 0xbfb8aa3b, v6
	v_exp_f32_e32 v5, v5
	v_div_fmas_f32 v0, v0, v18, v19
	v_div_fixup_f32 v0, v0, v4, v22
	v_lshlrev_b64 v[2:3], 9, v[2:3]
	v_add_f32_e32 v4, 1.0, v5
	v_div_scale_f32 v5, s[4:5], v4, v4, v6
	v_rcp_f32_e32 v18, v5
	v_cvt_pk_bf16_f32 v0, v0, s0
	v_lshl_add_u64 v[2:3], v[66:67], 0, v[2:3]
	global_store_short v[2:3], v0, off
	v_fma_f32 v0, -v5, v18, 1.0
	v_fmac_f32_e32 v18, v0, v18
	v_div_scale_f32 v0, vcc, v6, v4, v6
	v_mul_f32_e32 v19, v0, v18
	v_fma_f32 v20, -v5, v19, v0
	v_fmac_f32_e32 v19, v20, v18
	v_fma_f32 v0, -v5, v19, v0
	v_mul_f32_e32 v5, 0xbfb8aa3b, v23
	v_exp_f32_e32 v5, v5
	v_div_fmas_f32 v0, v0, v18, v19
	v_div_fixup_f32 v0, v0, v4, v6
	v_cvt_pk_bf16_f32 v0, v0, s0
	v_add_f32_e32 v4, 1.0, v5
	v_div_scale_f32 v5, s[4:5], v4, v4, v23
	v_rcp_f32_e32 v6, v5
	global_store_short v[2:3], v0, off offset:64
	v_or_b32_e32 v2, 41, v68
	v_ashrrev_i32_e32 v3, 31, v2
	v_fma_f32 v0, -v5, v6, 1.0
	v_fmac_f32_e32 v6, v0, v6
	v_div_scale_f32 v0, vcc, v23, v4, v23
	v_mul_f32_e32 v18, v0, v6
	v_fma_f32 v19, -v5, v18, v0
	v_fmac_f32_e32 v18, v19, v6
	v_fma_f32 v0, -v5, v18, v0
	v_mul_f32_e32 v5, 0xbfb8aa3b, v7
	v_exp_f32_e32 v5, v5
	v_div_fmas_f32 v0, v0, v6, v18
	v_div_fixup_f32 v0, v0, v4, v23
	v_lshlrev_b64 v[2:3], 9, v[2:3]
	v_add_f32_e32 v4, 1.0, v5
	v_div_scale_f32 v5, s[4:5], v4, v4, v7
	v_rcp_f32_e32 v6, v5
	v_cvt_pk_bf16_f32 v0, v0, s0
	v_lshl_add_u64 v[2:3], v[66:67], 0, v[2:3]
	global_store_short v[2:3], v0, off
	v_fma_f32 v0, -v5, v6, 1.0
	v_fmac_f32_e32 v6, v0, v6
	v_div_scale_f32 v0, vcc, v7, v4, v7
	v_mul_f32_e32 v18, v0, v6
	v_fma_f32 v19, -v5, v18, v0
	v_fmac_f32_e32 v18, v19, v6
	v_fma_f32 v0, -v5, v18, v0
	v_mul_f32_e32 v5, 0xbfb8aa3b, v24
	v_exp_f32_e32 v5, v5
	v_div_fmas_f32 v0, v0, v6, v18
	v_div_fixup_f32 v0, v0, v4, v7
	v_cvt_pk_bf16_f32 v0, v0, s0
	v_add_f32_e32 v4, 1.0, v5
	v_div_scale_f32 v5, s[4:5], v4, v4, v24
	v_rcp_f32_e32 v6, v5
	global_store_short v[2:3], v0, off offset:64
	v_or_b32_e32 v2, 42, v68
	v_ashrrev_i32_e32 v3, 31, v2
	v_fma_f32 v0, -v5, v6, 1.0
	v_fmac_f32_e32 v6, v0, v6
	v_div_scale_f32 v0, vcc, v24, v4, v24
	v_mul_f32_e32 v7, v0, v6
	v_fma_f32 v18, -v5, v7, v0
	v_fmac_f32_e32 v7, v18, v6
	v_fma_f32 v0, -v5, v7, v0
	v_mul_f32_e32 v5, 0xbfb8aa3b, v8
	v_exp_f32_e32 v5, v5
	v_div_fmas_f32 v0, v0, v6, v7
	v_div_fixup_f32 v0, v0, v4, v24
	v_lshlrev_b64 v[2:3], 9, v[2:3]
	v_add_f32_e32 v4, 1.0, v5
	v_div_scale_f32 v5, s[4:5], v4, v4, v8
	v_rcp_f32_e32 v6, v5
	v_cvt_pk_bf16_f32 v0, v0, s0
	v_lshl_add_u64 v[2:3], v[66:67], 0, v[2:3]
	global_store_short v[2:3], v0, off
	v_fma_f32 v0, -v5, v6, 1.0
	v_fmac_f32_e32 v6, v0, v6
	v_div_scale_f32 v0, vcc, v8, v4, v8
	v_mul_f32_e32 v7, v0, v6
	v_fma_f32 v18, -v5, v7, v0
	v_fmac_f32_e32 v7, v18, v6
	v_fma_f32 v0, -v5, v7, v0
	v_mul_f32_e32 v5, 0xbfb8aa3b, v25
	v_exp_f32_e32 v5, v5
	v_div_fmas_f32 v0, v0, v6, v7
	v_div_fixup_f32 v0, v0, v4, v8
	v_cvt_pk_bf16_f32 v0, v0, s0
	v_add_f32_e32 v4, 1.0, v5
	v_div_scale_f32 v5, s[4:5], v4, v4, v25
	v_rcp_f32_e32 v6, v5
	global_store_short v[2:3], v0, off offset:64
	v_or_b32_e32 v2, 43, v68
	v_ashrrev_i32_e32 v3, 31, v2
	v_fma_f32 v0, -v5, v6, 1.0
	v_fmac_f32_e32 v6, v0, v6
	v_div_scale_f32 v0, vcc, v25, v4, v25
	v_mul_f32_e32 v7, v0, v6
	v_fma_f32 v8, -v5, v7, v0
	v_fmac_f32_e32 v7, v8, v6
	v_fma_f32 v0, -v5, v7, v0
	v_mul_f32_e32 v5, 0xbfb8aa3b, v9
	v_exp_f32_e32 v5, v5
	v_div_fmas_f32 v0, v0, v6, v7
	v_div_fixup_f32 v0, v0, v4, v25
	v_lshlrev_b64 v[2:3], 9, v[2:3]
	v_add_f32_e32 v4, 1.0, v5
	v_div_scale_f32 v5, s[4:5], v4, v4, v9
	v_rcp_f32_e32 v6, v5
	v_cvt_pk_bf16_f32 v0, v0, s0
	v_lshl_add_u64 v[2:3], v[66:67], 0, v[2:3]
	global_store_short v[2:3], v0, off
	v_fma_f32 v0, -v5, v6, 1.0
	v_fmac_f32_e32 v6, v0, v6
	v_div_scale_f32 v0, vcc, v9, v4, v9
	v_mul_f32_e32 v7, v0, v6
	v_fma_f32 v8, -v5, v7, v0
	v_fmac_f32_e32 v7, v8, v6
	v_fma_f32 v0, -v5, v7, v0
	v_mul_f32_e32 v5, 0xbfb8aa3b, v26
	v_exp_f32_e32 v5, v5
	v_div_fmas_f32 v0, v0, v6, v7
	v_div_fixup_f32 v0, v0, v4, v9
	v_cvt_pk_bf16_f32 v0, v0, s0
	v_add_f32_e32 v4, 1.0, v5
	v_div_scale_f32 v5, s[4:5], v4, v4, v26
	v_rcp_f32_e32 v6, v5
	global_store_short v[2:3], v0, off offset:64
	v_or_b32_e32 v2, 48, v68
	v_ashrrev_i32_e32 v3, 31, v2
	v_fma_f32 v0, -v5, v6, 1.0
	v_fmac_f32_e32 v6, v0, v6
	v_div_scale_f32 v0, vcc, v26, v4, v26
	v_mul_f32_e32 v7, v0, v6
	v_fma_f32 v8, -v5, v7, v0
	v_fmac_f32_e32 v7, v8, v6
	v_fma_f32 v0, -v5, v7, v0
	v_mul_f32_e32 v5, 0xbfb8aa3b, v10
	v_exp_f32_e32 v5, v5
	v_div_fmas_f32 v0, v0, v6, v7
	v_div_fixup_f32 v0, v0, v4, v26
	v_lshlrev_b64 v[2:3], 9, v[2:3]
	v_add_f32_e32 v4, 1.0, v5
	v_div_scale_f32 v5, s[4:5], v4, v4, v10
	v_rcp_f32_e32 v6, v5
	v_cvt_pk_bf16_f32 v0, v0, s0
	v_lshl_add_u64 v[2:3], v[66:67], 0, v[2:3]
	global_store_short v[2:3], v0, off
	v_fma_f32 v0, -v5, v6, 1.0
	v_fmac_f32_e32 v6, v0, v6
	v_div_scale_f32 v0, vcc, v10, v4, v10
	v_mul_f32_e32 v7, v0, v6
	v_fma_f32 v8, -v5, v7, v0
	v_fmac_f32_e32 v7, v8, v6
	v_fma_f32 v0, -v5, v7, v0
	v_mul_f32_e32 v5, 0xbfb8aa3b, v27
	v_exp_f32_e32 v5, v5
	v_div_fmas_f32 v0, v0, v6, v7
	v_div_fixup_f32 v0, v0, v4, v10
	v_cvt_pk_bf16_f32 v0, v0, s0
	v_add_f32_e32 v4, 1.0, v5
	v_div_scale_f32 v5, s[4:5], v4, v4, v27
	v_rcp_f32_e32 v6, v5
	global_store_short v[2:3], v0, off offset:64
	v_or_b32_e32 v2, 49, v68
	v_ashrrev_i32_e32 v3, 31, v2
	v_fma_f32 v0, -v5, v6, 1.0
	v_fmac_f32_e32 v6, v0, v6
	v_div_scale_f32 v0, vcc, v27, v4, v27
	v_mul_f32_e32 v7, v0, v6
	v_fma_f32 v8, -v5, v7, v0
	v_fmac_f32_e32 v7, v8, v6
	v_fma_f32 v0, -v5, v7, v0
	v_mul_f32_e32 v5, 0xbfb8aa3b, v11
	v_exp_f32_e32 v5, v5
	v_div_fmas_f32 v0, v0, v6, v7
	v_div_fixup_f32 v0, v0, v4, v27
	v_lshlrev_b64 v[2:3], 9, v[2:3]
	v_add_f32_e32 v4, 1.0, v5
	v_div_scale_f32 v5, s[4:5], v4, v4, v11
	v_rcp_f32_e32 v6, v5
	v_cvt_pk_bf16_f32 v0, v0, s0
	v_lshl_add_u64 v[2:3], v[66:67], 0, v[2:3]
	global_store_short v[2:3], v0, off
	v_fma_f32 v0, -v5, v6, 1.0
	v_fmac_f32_e32 v6, v0, v6
	v_div_scale_f32 v0, vcc, v11, v4, v11
	v_mul_f32_e32 v7, v0, v6
	v_fma_f32 v8, -v5, v7, v0
	v_fmac_f32_e32 v7, v8, v6
	v_fma_f32 v0, -v5, v7, v0
	v_mul_f32_e32 v5, 0xbfb8aa3b, v28
	v_exp_f32_e32 v5, v5
	v_div_fmas_f32 v0, v0, v6, v7
	v_div_fixup_f32 v0, v0, v4, v11
	v_cvt_pk_bf16_f32 v0, v0, s0
	v_add_f32_e32 v4, 1.0, v5
	v_div_scale_f32 v5, s[4:5], v4, v4, v28
	v_rcp_f32_e32 v6, v5
	global_store_short v[2:3], v0, off offset:64
	v_or_b32_e32 v2, 50, v68
	v_ashrrev_i32_e32 v3, 31, v2
	v_fma_f32 v0, -v5, v6, 1.0
	v_fmac_f32_e32 v6, v0, v6
	v_div_scale_f32 v0, vcc, v28, v4, v28
	v_mul_f32_e32 v7, v0, v6
	v_fma_f32 v8, -v5, v7, v0
	v_fmac_f32_e32 v7, v8, v6
	v_fma_f32 v0, -v5, v7, v0
	v_mul_f32_e32 v5, 0xbfb8aa3b, v12
	v_exp_f32_e32 v5, v5
	v_div_fmas_f32 v0, v0, v6, v7
	v_div_fixup_f32 v0, v0, v4, v28
	v_lshlrev_b64 v[2:3], 9, v[2:3]
	v_add_f32_e32 v4, 1.0, v5
	v_div_scale_f32 v5, s[4:5], v4, v4, v12
	v_rcp_f32_e32 v6, v5
	v_cvt_pk_bf16_f32 v0, v0, s0
	v_lshl_add_u64 v[2:3], v[66:67], 0, v[2:3]
	global_store_short v[2:3], v0, off
	v_fma_f32 v0, -v5, v6, 1.0
	v_fmac_f32_e32 v6, v0, v6
	v_div_scale_f32 v0, vcc, v12, v4, v12
	v_mul_f32_e32 v7, v0, v6
	v_fma_f32 v8, -v5, v7, v0
	v_fmac_f32_e32 v7, v8, v6
	v_fma_f32 v0, -v5, v7, v0
	v_mul_f32_e32 v5, 0xbfb8aa3b, v29
	v_exp_f32_e32 v5, v5
	v_div_fmas_f32 v0, v0, v6, v7
	v_div_fixup_f32 v0, v0, v4, v12
	v_cvt_pk_bf16_f32 v0, v0, s0
	v_add_f32_e32 v4, 1.0, v5
	v_div_scale_f32 v5, s[4:5], v4, v4, v29
	v_rcp_f32_e32 v6, v5
	global_store_short v[2:3], v0, off offset:64
	v_or_b32_e32 v2, 51, v68
	v_ashrrev_i32_e32 v3, 31, v2
	v_fma_f32 v0, -v5, v6, 1.0
	v_fmac_f32_e32 v6, v0, v6
	v_div_scale_f32 v0, vcc, v29, v4, v29
	v_mul_f32_e32 v7, v0, v6
	v_fma_f32 v8, -v5, v7, v0
	v_fmac_f32_e32 v7, v8, v6
	v_fma_f32 v0, -v5, v7, v0
	v_mul_f32_e32 v5, 0xbfb8aa3b, v13
	v_exp_f32_e32 v5, v5
	v_div_fmas_f32 v0, v0, v6, v7
	v_div_fixup_f32 v0, v0, v4, v29
	v_lshlrev_b64 v[2:3], 9, v[2:3]
	v_add_f32_e32 v4, 1.0, v5
	v_div_scale_f32 v5, s[4:5], v4, v4, v13
	v_rcp_f32_e32 v6, v5
	v_cvt_pk_bf16_f32 v0, v0, s0
	v_lshl_add_u64 v[2:3], v[66:67], 0, v[2:3]
	global_store_short v[2:3], v0, off
	v_fma_f32 v0, -v5, v6, 1.0
	v_fmac_f32_e32 v6, v0, v6
	v_div_scale_f32 v0, vcc, v13, v4, v13
	v_mul_f32_e32 v7, v0, v6
	v_fma_f32 v8, -v5, v7, v0
	v_fmac_f32_e32 v7, v8, v6
	v_fma_f32 v0, -v5, v7, v0
	v_mul_f32_e32 v5, 0xbfb8aa3b, v30
	v_exp_f32_e32 v5, v5
	v_div_fmas_f32 v0, v0, v6, v7
	v_div_fixup_f32 v0, v0, v4, v13
	v_cvt_pk_bf16_f32 v0, v0, s0
	v_add_f32_e32 v4, 1.0, v5
	v_div_scale_f32 v5, s[4:5], v4, v4, v30
	v_rcp_f32_e32 v6, v5
	global_store_short v[2:3], v0, off offset:64
	v_or_b32_e32 v2, 56, v68
	v_ashrrev_i32_e32 v3, 31, v2
	v_fma_f32 v0, -v5, v6, 1.0
	v_fmac_f32_e32 v6, v0, v6
	v_div_scale_f32 v0, vcc, v30, v4, v30
	v_mul_f32_e32 v7, v0, v6
	v_fma_f32 v8, -v5, v7, v0
	v_fmac_f32_e32 v7, v8, v6
	v_fma_f32 v0, -v5, v7, v0
	v_mul_f32_e32 v5, 0xbfb8aa3b, v14
	v_exp_f32_e32 v5, v5
	v_div_fmas_f32 v0, v0, v6, v7
	v_div_fixup_f32 v0, v0, v4, v30
	v_lshlrev_b64 v[2:3], 9, v[2:3]
	v_add_f32_e32 v4, 1.0, v5
	v_div_scale_f32 v5, s[4:5], v4, v4, v14
	v_rcp_f32_e32 v6, v5
	v_cvt_pk_bf16_f32 v0, v0, s0
	v_lshl_add_u64 v[2:3], v[66:67], 0, v[2:3]
	global_store_short v[2:3], v0, off
	v_fma_f32 v0, -v5, v6, 1.0
	v_fmac_f32_e32 v6, v0, v6
	v_div_scale_f32 v0, vcc, v14, v4, v14
	v_mul_f32_e32 v7, v0, v6
	v_fma_f32 v8, -v5, v7, v0
	v_fmac_f32_e32 v7, v8, v6
	v_fma_f32 v0, -v5, v7, v0
	v_mul_f32_e32 v5, 0xbfb8aa3b, v31
	v_exp_f32_e32 v5, v5
	v_div_fmas_f32 v0, v0, v6, v7
	v_div_fixup_f32 v0, v0, v4, v14
	v_cvt_pk_bf16_f32 v0, v0, s0
	v_add_f32_e32 v4, 1.0, v5
	v_div_scale_f32 v5, s[4:5], v4, v4, v31
	v_rcp_f32_e32 v6, v5
	global_store_short v[2:3], v0, off offset:64
	v_or_b32_e32 v2, 57, v68
	v_ashrrev_i32_e32 v3, 31, v2
	v_fma_f32 v0, -v5, v6, 1.0
	v_fmac_f32_e32 v6, v0, v6
	v_div_scale_f32 v0, vcc, v31, v4, v31
	v_mul_f32_e32 v7, v0, v6
	v_fma_f32 v8, -v5, v7, v0
	v_fmac_f32_e32 v7, v8, v6
	v_fma_f32 v0, -v5, v7, v0
	v_mul_f32_e32 v5, 0xbfb8aa3b, v15
	v_exp_f32_e32 v5, v5
	v_div_fmas_f32 v0, v0, v6, v7
	v_div_fixup_f32 v0, v0, v4, v31
	v_lshlrev_b64 v[2:3], 9, v[2:3]
	v_add_f32_e32 v4, 1.0, v5
	v_div_scale_f32 v5, s[4:5], v4, v4, v15
	v_rcp_f32_e32 v6, v5
	v_cvt_pk_bf16_f32 v0, v0, s0
	v_lshl_add_u64 v[2:3], v[66:67], 0, v[2:3]
	global_store_short v[2:3], v0, off
	v_fma_f32 v0, -v5, v6, 1.0
	v_fmac_f32_e32 v6, v0, v6
	v_div_scale_f32 v0, vcc, v15, v4, v15
	v_mul_f32_e32 v7, v0, v6
	v_fma_f32 v8, -v5, v7, v0
	v_fmac_f32_e32 v7, v8, v6
	v_fma_f32 v0, -v5, v7, v0
	v_mul_f32_e32 v5, 0xbfb8aa3b, v32
	v_exp_f32_e32 v5, v5
	v_div_fmas_f32 v0, v0, v6, v7
	v_div_fixup_f32 v0, v0, v4, v15
	v_cvt_pk_bf16_f32 v0, v0, s0
	v_add_f32_e32 v4, 1.0, v5
	v_div_scale_f32 v5, s[4:5], v4, v4, v32
	v_rcp_f32_e32 v6, v5
	global_store_short v[2:3], v0, off offset:64
	v_or_b32_e32 v2, 58, v68
	v_ashrrev_i32_e32 v3, 31, v2
	v_fma_f32 v0, -v5, v6, 1.0
	v_fmac_f32_e32 v6, v0, v6
	v_div_scale_f32 v0, vcc, v32, v4, v32
	v_mul_f32_e32 v7, v0, v6
	v_fma_f32 v8, -v5, v7, v0
	v_fmac_f32_e32 v7, v8, v6
	v_fma_f32 v0, -v5, v7, v0
	v_mul_f32_e32 v5, 0xbfb8aa3b, v16
	v_exp_f32_e32 v5, v5
	v_div_fmas_f32 v0, v0, v6, v7
	v_div_fixup_f32 v0, v0, v4, v32
	v_lshlrev_b64 v[2:3], 9, v[2:3]
	v_add_f32_e32 v4, 1.0, v5
	v_div_scale_f32 v5, s[4:5], v4, v4, v16
	v_rcp_f32_e32 v6, v5
	v_cvt_pk_bf16_f32 v0, v0, s0
	v_lshl_add_u64 v[2:3], v[66:67], 0, v[2:3]
	global_store_short v[2:3], v0, off
	v_fma_f32 v0, -v5, v6, 1.0
	v_fmac_f32_e32 v6, v0, v6
	v_div_scale_f32 v0, vcc, v16, v4, v16
	v_mul_f32_e32 v7, v0, v6
	v_fma_f32 v8, -v5, v7, v0
	v_fmac_f32_e32 v7, v8, v6
	v_fma_f32 v0, -v5, v7, v0
	v_mul_f32_e32 v5, 0xbfb8aa3b, v33
	v_exp_f32_e32 v5, v5
	v_div_fmas_f32 v0, v0, v6, v7
	v_div_fixup_f32 v0, v0, v4, v16
	v_cvt_pk_bf16_f32 v0, v0, s0
	v_add_f32_e32 v4, 1.0, v5
	v_div_scale_f32 v5, s[4:5], v4, v4, v33
	v_rcp_f32_e32 v6, v5
	global_store_short v[2:3], v0, off offset:64
	v_or_b32_e32 v2, 59, v68
	v_ashrrev_i32_e32 v3, 31, v2
	v_fma_f32 v0, -v5, v6, 1.0
	v_fmac_f32_e32 v6, v0, v6
	v_div_scale_f32 v0, vcc, v33, v4, v33
	v_mul_f32_e32 v7, v0, v6
	v_fma_f32 v8, -v5, v7, v0
	v_fmac_f32_e32 v7, v8, v6
	v_fma_f32 v0, -v5, v7, v0
	v_mul_f32_e32 v5, 0xbfb8aa3b, v17
	v_exp_f32_e32 v5, v5
	v_div_fmas_f32 v0, v0, v6, v7
	v_div_fixup_f32 v0, v0, v4, v33
	v_lshlrev_b64 v[2:3], 9, v[2:3]
	v_add_f32_e32 v4, 1.0, v5
	v_div_scale_f32 v5, s[4:5], v4, v4, v17
	v_rcp_f32_e32 v6, v5
	v_cvt_pk_bf16_f32 v0, v0, s0
	v_lshl_add_u64 v[2:3], v[66:67], 0, v[2:3]
	global_store_short v[2:3], v0, off
	v_fma_f32 v0, -v5, v6, 1.0
	v_fmac_f32_e32 v6, v0, v6
	v_div_scale_f32 v0, vcc, v17, v4, v17
	v_mul_f32_e32 v7, v0, v6
	v_fma_f32 v8, -v5, v7, v0
	v_fmac_f32_e32 v7, v8, v6
	v_fma_f32 v0, -v5, v7, v0
	v_div_fmas_f32 v0, v0, v6, v7
	v_div_fixup_f32 v0, v0, v4, v17
	v_cvt_pk_bf16_f32 v0, v0, s0
	global_store_short v[2:3], v0, off offset:64
